# phase-0 context K/V cache conversion items: all chunk loads (with address arithmetic) hoisted to the top of the item into spare registers by live-range renaming, one wait instead of five serialized ro
# speedup vs baseline: 1.0034x; 1.0034x over previous
.LBB0_1315:
	s_cmpk_gt_i32 s2, 0x13f
	s_cbranch_scc0 .LBB0_1324
	s_cmpk_gt_u32 s2, 0x24f
	s_cbranch_scc0 .LBB0_1325
	s_cmpk_gt_u32 s2, 0xacf
	s_mov_b64 s[0:1], -1
	s_cbranch_scc0 .LBB0_1319
	s_add_i32 s0, s2, 0xfffff530
	s_lshr_b32 s1, s0, 6
	s_lshl_b32 s22, s2, 6
	v_mov_b32_e32 v1, v184
	s_and_b32 s22, s22, 0x1c0
	s_lshl_b32 s23, s1, 9
	s_or_b32 s23, s23, s22
	v_lshlrev_b32_e32 v2, 2, v1
	v_ashrrev_i32_e32 v20, 4, v1
	v_and_b32_e32 v8, 60, v2
	v_add_u32_e32 v2, s23, v20
	s_bfe_u32 s0, s0, 0x30003
	v_lshlrev_b32_e32 v18, 2, v8
	v_ashrrev_i32_e32 v3, 31, v2
	v_lshlrev_b64 v[6:7], 11, v[2:3]
	v_lshl_or_b32 v19, s0, 8, v18
	v_readlane_b32 s36, v248, 6
	v_or_b32_e32 v6, v6, v19
	v_readlane_b32 s40, v248, 10
	v_readlane_b32 s41, v248, 11
	s_lshl_b32 s1, s1, 3
	v_add_u32_e32 v34, 0x100, v1
	v_lshl_add_u64 v[2:3], s[40:41], 0, v[6:7]
	global_load_dwordx4 v[2:5], v[2:3], off
	s_or_b32 s24, s1, s0
	v_ashrrev_i32_e32 v22, 4, v34
	s_lshl_b64 s[0:1], s[24:25], 9
	v_readlane_b32 s4, v246, 38
	v_mov_b32_e32 v9, v0
	v_ashrrev_i32_e32 v21, 31, v20
	v_lshlrev_b32_e32 v8, 1, v8
	v_add_u32_e32 v10, s23, v22
	s_or_b32 s0, s0, s22
	v_readlane_b32 s5, v246, 39
	v_ashrrev_i32_e32 v11, 31, v10
	v_lshlrev_b64 v[10:11], 11, v[10:11]
	v_lshl_add_u64 v[14:15], s[4:5], 0, v[8:9]
	v_lshl_add_u64 v[8:9], s[0:1], 0, v[20:21]
	v_lshlrev_b64 v[8:9], 7, v[8:9]
	v_or_b32_e32 v10, v10, v19
	v_lshl_add_u64 v[8:9], v[14:15], 0, v[8:9]
	v_lshl_add_u64 v[12:13], s[40:41], 0, v[10:11]
	v_ashrrev_i32_e32 v23, 31, v22
	v_readlane_b32 s42, v248, 12
	v_readlane_b32 s43, v248, 13
	s_movk_i32 s4, 0x104
	v_readlane_b32 s37, v248, 7
	v_lshl_add_u64 v[6:7], s[42:43], 0, v[6:7]
	v_lshl_add_u64 v[10:11], s[42:43], 0, v[10:11]
	v_readlane_b32 s38, v248, 8
	v_readlane_b32 s39, v248, 9
	v_readlane_b32 s44, v248, 14
	v_readlane_b32 s45, v248, 15
	v_readlane_b32 s46, v248, 16
	v_readlane_b32 s47, v248, 17
	v_readlane_b32 s48, v248, 18
	v_readlane_b32 s49, v248, 19
	v_readlane_b32 s50, v248, 20
	v_readlane_b32 s51, v248, 21
	global_load_dwordx4 v[40:43], v[12:13], off
	global_load_dwordx4 v[44:47], v[6:7], off
	v_add_u32_e32 v48, 0x200, v1
	v_ashrrev_i32_e32 v56, 4, v48
	v_add_u32_e32 v48, s23, v56
	v_ashrrev_i32_e32 v49, 31, v48
	v_lshlrev_b64 v[52:53], 11, v[48:49]
	v_or_b32_e32 v52, v52, v19
	v_lshl_add_u64 v[60:61], s[40:41], 0, v[52:53]
	global_load_dwordx4 v[64:67], v[60:61], off
	global_load_dwordx4 v[68:71], v[10:11], off
	v_add_u32_e32 v72, 0x300, v1
	v_ashrrev_i32_e32 v76, 4, v72
	v_add_u32_e32 v72, s23, v76
	v_ashrrev_i32_e32 v73, 31, v72
	v_lshlrev_b64 v[80:81], 11, v[72:73]
	v_or_b32_e32 v80, v80, v19
	v_lshl_add_u64 v[82:83], s[40:41], 0, v[80:81]
	global_load_dwordx4 v[86:89], v[82:83], off
	v_add_u32_e32 v90, 0x200, v1
	v_ashrrev_i32_e32 v98, 4, v90
	v_add_u32_e32 v90, s23, v98
	v_ashrrev_i32_e32 v91, 31, v90
	v_lshlrev_b64 v[94:95], 11, v[90:91]
	v_or_b32_e32 v94, v94, v19
	v_lshl_add_u64 v[94:95], s[42:43], 0, v[94:95]
	global_load_dwordx4 v[102:105], v[94:95], off
	v_add_u32_e32 v106, 0x300, v1
	v_ashrrev_i32_e32 v110, 4, v106
	v_add_u32_e32 v106, s23, v110
	v_ashrrev_i32_e32 v107, 31, v106
	v_lshlrev_b64 v[114:115], 11, v[106:107]
	v_or_b32_e32 v114, v114, v19
	v_lshl_add_u64 v[114:115], s[42:43], 0, v[114:115]
	global_load_dwordx4 v[118:121], v[114:115], off
	s_waitcnt vmcnt(0)
	v_cvt_pk_bf16_f32 v2, v2, v3
	v_cvt_pk_bf16_f32 v3, v4, v5
	global_store_dwordx2 v[8:9], v[2:3], off
	v_add_u32_e32 v8, 0x200, v1
	v_ashrrev_i32_e32 v24, 4, v8
	v_add_u32_e32 v8, s23, v24
	v_ashrrev_i32_e32 v9, 31, v8
	v_lshl_add_u64 v[12:13], s[0:1], 0, v[22:23]
	v_lshlrev_b64 v[16:17], 11, v[8:9]
	v_lshlrev_b64 v[8:9], 7, v[12:13]
	v_or_b32_e32 v16, v16, v19
	v_lshl_add_u64 v[12:13], v[14:15], 0, v[8:9]
	v_lshl_add_u64 v[26:27], s[40:41], 0, v[16:17]
	v_ashrrev_i32_e32 v25, 31, v24
	v_lshl_add_u64 v[28:29], s[0:1], 0, v[24:25]
	v_lshl_add_u64 v[16:17], s[42:43], 0, v[16:17]
	s_nop 0
	v_cvt_pk_bf16_f32 v2, v40, v41
	v_cvt_pk_bf16_f32 v3, v42, v43
	global_store_dwordx2 v[12:13], v[2:3], off
	v_add_u32_e32 v12, 0x300, v1
	v_ashrrev_i32_e32 v26, 4, v12
	v_add_u32_e32 v12, s23, v26
	v_ashrrev_i32_e32 v13, 31, v12
	v_lshlrev_b64 v[30:31], 11, v[12:13]
	v_lshlrev_b64 v[12:13], 7, v[28:29]
	v_or_b32_e32 v30, v30, v19
	v_lshl_add_u64 v[28:29], v[14:15], 0, v[12:13]
	v_lshl_add_u64 v[32:33], s[40:41], 0, v[30:31]
	v_ashrrev_i32_e32 v27, 31, v26
	v_lshl_add_u64 v[30:31], s[42:43], 0, v[30:31]
	v_lshlrev_b32_e32 v19, 3, v1
	v_mad_u64_u32 v[20:21], s[28:29], v20, s4, v[18:19]
	v_mad_u64_u32 v[22:23], s[28:29], v22, s4, v[18:19]
	v_mad_u64_u32 v[24:25], s[28:29], v24, s4, v[18:19]
	s_movk_i32 s43, 0x1fff
	s_nop 0
	v_cvt_pk_bf16_f32 v2, v64, v65
	v_cvt_pk_bf16_f32 v3, v66, v67
	global_store_dwordx2 v[28:29], v[2:3], off
	v_lshl_add_u64 v[28:29], s[0:1], 0, v[26:27]
	v_lshlrev_b64 v[28:29], 7, v[28:29]
	v_lshl_add_u64 v[28:29], v[14:15], 0, v[28:29]
	v_ashrrev_i32_e32 v32, 3, v34
	s_lshl_b64 s[0:1], s[24:25], 16
	v_ashrrev_i32_e32 v33, 31, v32
	s_nop 0
	v_cvt_pk_bf16_f32 v2, v86, v87
	v_cvt_pk_bf16_f32 v3, v88, v89
	global_store_dwordx2 v[28:29], v[2:3], off
	v_ashrrev_i32_e32 v30, 3, v1
	v_and_b32_e32 v1, 56, v19
	v_lshlrev_b32_e32 v28, 1, v1
	v_mul_u32_u24_e32 v1, 0x104, v1
	v_mad_u64_u32 v[18:19], s[28:29], v26, s4, v[18:19]
	v_readlane_b32 s4, v246, 58
	v_lshl_add_u32 v19, v30, 2, v1
	v_lshl_add_u32 v1, v32, 2, v1
	s_add_u32 s0, s4, s0
	v_readlane_b32 s4, v246, 60
	v_add_u32_e32 v21, 0x400, v19
	v_add_u32_e32 v23, 0x400, v1
	s_addc_u32 s1, s4, s1
	s_lshl_b32 s22, s22, 1
	s_add_u32 s0, s0, s22
	v_mov_b32_e32 v29, v0
	v_ashrrev_i32_e32 v31, 31, v30
	s_addc_u32 s1, s1, 0
	v_lshlrev_b64 v[34:35], 10, v[30:31]
	v_lshl_add_u64 v[28:29], s[0:1], 0, v[28:29]
	v_lshlrev_b64 v[26:27], 10, v[32:33]
	v_lshl_add_u64 v[30:31], v[28:29], 0, v[34:35]
	v_lshl_add_u64 v[26:27], v[28:29], 0, v[26:27]
	s_mov_b64 s[0:1], 0
	ds_write2_b32 v20, v44, v45 offset1:1
	ds_write2_b32 v20, v46, v47 offset0:2 offset1:3
	ds_write2_b32 v22, v68, v69 offset1:1
	ds_write2_b32 v22, v70, v71 offset0:2 offset1:3
	s_nop 0
	ds_write2_b32 v24, v102, v103 offset1:1
	ds_write2_b32 v24, v104, v105 offset0:2 offset1:3
	s_nop 0
	ds_write2_b32 v18, v118, v119 offset1:1
	ds_write2_b32 v18, v120, v121 offset0:2 offset1:3
	s_waitcnt lgkmcnt(0)
	s_barrier
	ds_read2_b32 v[2:3], v19 offset1:65
	ds_read2_b32 v[4:5], v19 offset0:130 offset1:195
	ds_read2_b32 v[6:7], v21 offset0:4 offset1:69
	ds_read2_b32 v[8:9], v21 offset0:134 offset1:199
	ds_read2_b32 v[10:11], v1 offset1:65
	ds_read2_b32 v[12:13], v1 offset0:130 offset1:195
	ds_read2_b32 v[14:15], v23 offset0:4 offset1:69
	ds_read2_b32 v[16:17], v23 offset0:134 offset1:199
	s_waitcnt lgkmcnt(7)
	v_cvt_pk_bf16_f32 v2, v2, v3
	s_waitcnt lgkmcnt(6)
	v_cvt_pk_bf16_f32 v3, v4, v5
	s_waitcnt lgkmcnt(5)
	v_cvt_pk_bf16_f32 v4, v6, v7
	s_waitcnt lgkmcnt(4)
	v_cvt_pk_bf16_f32 v5, v8, v9
	s_waitcnt lgkmcnt(3)
	v_cvt_pk_bf16_f32 v6, v10, v11
	s_waitcnt lgkmcnt(2)
	v_cvt_pk_bf16_f32 v7, v12, v13
	s_waitcnt lgkmcnt(1)
	v_cvt_pk_bf16_f32 v8, v14, v15
	s_waitcnt lgkmcnt(0)
	v_cvt_pk_bf16_f32 v9, v16, v17
	global_store_dwordx4 v[30:31], v[2:5], off
	global_store_dwordx4 v[26:27], v[6:9], off
	s_barrier
